# v25 + attention loops: wait for the first V^T fragment batch moved from right after the first exp to just before the first PV MFMA as a counted lgkmcnt (exps now run under the LDS latency)
# speedup vs baseline: 1.0067x; 1.0005x over previous
; #define ALAS __attribute__((address_space(3)))
; __device__ __forceinline__ float ex2(float x) { return __builtin_amdgcn_exp2f(x); }
; template <int NDB> __device__ __forceinline__ void wait_v(bf16x8 (&v)[2 * NDB]) { if constexpr (NDB == 4) lds_wait8(v); else lds_wait4(v); }
; template <int NDB>
; __device__ __forceinline__ void softmax_pv(f32x16& s0, f32x16& s1, float& mref, float& lsum, f32x16 (&o)[NDB], const ALAS unsigned char* Vb, int r32, int hi) {
;     const unsigned vp = (unsigned)(uintptr_t)(Vb + r32 * ROWB + hi * 16);
;     bf16x8 va[2 * NDB], vb[2 * NDB];
;     issue_v<NDB, 0>(va, vp);
;     float ps = 0.f;
; #pragma unroll
;     for (int r = 0; r < 16; ++r) { s0[r] = ex2(s0[r]); ps += s0[r]; }
;     bf16x8 pf0, pf1, pf2, pf3;
;     pack16(s0, pf0, pf1);
;     wait_v<NDB>(va);
;     issue_v<NDB, 1>(vb, vp);
;     __builtin_amdgcn_sched_barrier(0);
; #pragma unroll
;     for (int d = 0; d < NDB; ++d) o[d] = __builtin_amdgcn_mfma_f32_32x32x16_bf16(va[d], pf0, o[d], 0, 0, 0);
; #pragma unroll
;     for (int d = 0; d < NDB; ++d) o[d] = __builtin_amdgcn_mfma_f32_32x32x16_bf16(va[NDB + d], pf1, o[d], 0, 0, 0);
; #pragma unroll
;     for (int r = 0; r < 16; ++r) { s1[r] = ex2(s1[r]); ps += s1[r]; }
;     pack16(s1, pf2, pf3);
; #pragma unroll
;     for (int i = 0; i < 2 * NDB; ++i) { __builtin_amdgcn_sched_group_barrier(0x008, 1, 0); __builtin_amdgcn_sched_group_barrier(0x002, (NDB == 4 ? 5 : 10), 0); }
;     __builtin_amdgcn_sched_barrier(0);
;     wait_v<NDB>(vb);
;     __builtin_amdgcn_sched_barrier(0);
; #pragma unroll
;     for (int d = 0; d < NDB; ++d) o[d] = __builtin_amdgcn_mfma_f32_32x32x16_bf16(vb[d], pf2, o[d], 0, 0, 0);
; #pragma unroll
;     for (int d = 0; d < NDB; ++d) o[d] = __builtin_amdgcn_mfma_f32_32x32x16_bf16(vb[NDB + d], pf3, o[d], 0, 0, 0);
;     lsum += ps;
;     if (__any(ps > 1048576.0f)) {
;         const float pt = ps + __shfl_xor(ps, 32); const float dl = pt > 1048576.0f ? floorf(__log2f(pt)) : 0.f, al = ex2(-dl); mref += dl; lsum *= al;
; #pragma unroll
;         for (int d = 0; d < NDB; ++d)
; #pragma unroll
;             for (int r = 0; r < 16; ++r) o[d][r] *= al;
;     }
.LBB0_509:
	v_add_u32_e32 v144, s18, v143
	v_add3_u32 v144, v144, v130, s35
	ds_read_b128 v[172:175], v144 offset:0
	ds_read_b128 v[176:179], v144 offset:4608
	ds_read_b128 v[180:183], v144 offset:9216
	ds_read_b128 v[184:187], v144 offset:13824
	ds_read_b128 v[188:191], v144 offset:32
	ds_read_b128 v[192:195], v144 offset:4640
	ds_read_b128 v[196:199], v144 offset:9248
	ds_read_b128 v[216:219], v144 offset:13856
	s_nop 7
	v_exp_f32_e32 v248, v88
	v_exp_f32_e32 v249, v89
	v_exp_f32_e32 v250, v90
	v_exp_f32_e32 v251, v91
	ds_read_b128 v[88:91], v144 offset:64
	v_exp_f32_e32 v252, v92
	v_exp_f32_e32 v253, v93
	v_exp_f32_e32 v215, v94
	v_exp_f32_e32 v207, v95
	ds_read_b128 v[92:95], v144 offset:4672
	ds_read_b128 v[220:223], v144 offset:9280
	ds_read_b128 v[224:227], v144 offset:13888
	ds_read_b128 v[228:231], v144 offset:96
	ds_read_b128 v[232:235], v144 offset:4704
	v_exp_f32_e32 v161, v80
	v_exp_f32_e32 v168, v81
	v_exp_f32_e32 v169, v82
	v_exp_f32_e32 v171, v83
	v_exp_f32_e32 v244, v84
	v_exp_f32_e32 v245, v85
	v_exp_f32_e32 v246, v86
	v_exp_f32_e32 v247, v87
	ds_read_b128 v[236:239], v144 offset:9312
	ds_read_b128 v[240:243], v144 offset:13920
	v_cvt_pk_bf16_f32 v80, v161, v168
	v_cvt_pk_bf16_f32 v81, v169, v171
	v_cvt_pk_bf16_f32 v82, v244, v245
	v_cvt_pk_bf16_f32 v83, v246, v247
	v_cvt_pk_bf16_f32 v84, v248, v249
	v_cvt_pk_bf16_f32 v85, v250, v251
	v_cvt_pk_bf16_f32 v86, v252, v253
	v_cvt_pk_bf16_f32 v87, v215, v207
	s_waitcnt lgkmcnt(8)
	v_mfma_f32_32x32x16_bf16 v[48:63], v[172:175], v[80:83], v[48:63]
	v_add_f32_e32 v144, 0, v161
	v_add_f32_e32 v144, v168, v144
	v_add_f32_e32 v144, v169, v144
	v_add_f32_e32 v144, v171, v144
	v_add_f32_e32 v144, v244, v144
	v_exp_f32_e32 v161, v68
	v_exp_f32_e32 v168, v69
	v_mfma_f32_32x32x16_bf16 v[32:47], v[176:179], v[80:83], v[32:47]
	v_add_f32_e32 v144, v245, v144
	v_add_f32_e32 v144, v246, v144
	v_add_f32_e32 v144, v247, v144
	v_add_f32_e32 v144, v248, v144
	v_add_f32_e32 v144, v249, v144
	v_exp_f32_e32 v169, v70
	v_exp_f32_e32 v171, v71
	v_mfma_f32_32x32x16_bf16 v[16:31], v[180:183], v[80:83], v[16:31]
	v_add_f32_e32 v144, v250, v144
	v_add_f32_e32 v144, v251, v144
	v_add_f32_e32 v144, v252, v144
	v_add_f32_e32 v144, v253, v144
	v_add_f32_e32 v144, v215, v144
	v_exp_f32_e32 v72, v72
	v_exp_f32_e32 v73, v73
	v_mfma_f32_32x32x16_bf16 v[0:15], v[184:187], v[80:83], v[0:15]
	v_exp_f32_e32 v81, v64
	v_exp_f32_e32 v82, v65
	v_exp_f32_e32 v83, v66
	v_add_f32_e32 v80, v207, v144
	v_exp_f32_e32 v144, v67
	v_add_f32_e32 v80, v81, v80
	v_add_f32_e32 v80, v82, v80
	v_exp_f32_e32 v74, v74
	v_exp_f32_e32 v75, v75
	v_exp_f32_e32 v76, v76
	v_exp_f32_e32 v77, v77
	v_exp_f32_e32 v78, v78
	v_exp_f32_e32 v79, v79
	v_add_f32_e32 v80, v83, v80
	v_add_f32_e32 v80, v144, v80
	v_add_f32_e32 v80, v161, v80
	v_add_f32_e32 v80, v168, v80
	v_cvt_pk_bf16_f32 v64, v81, v82
	v_cvt_pk_bf16_f32 v65, v83, v144
	v_cvt_pk_bf16_f32 v66, v161, v168
	v_cvt_pk_bf16_f32 v67, v169, v171
	v_mfma_f32_32x32x16_bf16 v[48:63], v[188:191], v[84:87], v[48:63]
	v_cvt_pk_bf16_f32 v68, v72, v73
	v_cvt_pk_bf16_f32 v69, v74, v75
	v_cvt_pk_bf16_f32 v70, v76, v77
	v_cvt_pk_bf16_f32 v71, v78, v79
	v_add_f32_e32 v80, v169, v80
	v_add_f32_e32 v80, v171, v80
	v_add_f32_e32 v72, v72, v80
	v_mfma_f32_32x32x16_bf16 v[32:47], v[192:195], v[84:87], v[32:47]
	v_add_f32_e32 v72, v73, v72
	v_add_f32_e32 v72, v74, v72
	v_add_f32_e32 v72, v75, v72
	v_add_f32_e32 v72, v76, v72
	v_add_f32_e32 v72, v77, v72
	v_add_f32_e32 v72, v78, v72
	v_mfma_f32_32x32x16_bf16 v[16:31], v[196:199], v[84:87], v[16:31]
	v_mfma_f32_32x32x16_bf16 v[0:15], v[216:219], v[84:87], v[0:15]
	s_waitcnt lgkmcnt(0)
	s_nop 0
	v_mfma_f32_32x32x16_bf16 v[48:63], v[88:91], v[64:67], v[48:63]
	v_mfma_f32_32x32x16_bf16 v[32:47], v[92:95], v[64:67], v[32:47]
	v_mfma_f32_32x32x16_bf16 v[16:31], v[220:223], v[64:67], v[16:31]
	v_mfma_f32_32x32x16_bf16 v[0:15], v[224:227], v[64:67], v[0:15]
	v_add_f32_e32 v64, v79, v72
	v_add_f32_e32 v162, v162, v64
	v_cmp_lt_f32_e32 vcc, s34, v64
	v_mfma_f32_32x32x16_bf16 v[48:63], v[228:231], v[68:71], v[48:63]
	v_mfma_f32_32x32x16_bf16 v[32:47], v[232:235], v[68:71], v[32:47]
	v_mfma_f32_32x32x16_bf16 v[16:31], v[236:239], v[68:71], v[16:31]
	v_mfma_f32_32x32x16_bf16 v[0:15], v[240:243], v[68:71], v[0:15]
	s_cbranch_vccz .LBB0_503
	ds_bpermute_b32 v65, v170, v64
	s_waitcnt lgkmcnt(0)
	v_add_f32_e32 v64, v64, v65
	v_log_f32_e32 v65, v64
	v_cmp_lt_f32_e32 vcc, s34, v64
	v_floor_f32_e32 v65, v65
	s_nop 0
	v_cndmask_b32_e32 v65, 0, v65, vcc
	v_exp_f32_e64 v64, -v65
	v_add_f32_e32 v163, v163, v65
	v_mul_f32_e32 v162, v162, v64
	v_pk_mul_f32 v[62:63], v[62:63], v[64:65] op_sel_hi:[1,0]
	v_pk_mul_f32 v[60:61], v[60:61], v[64:65] op_sel_hi:[1,0]
	v_pk_mul_f32 v[58:59], v[58:59], v[64:65] op_sel_hi:[1,0]
	v_pk_mul_f32 v[56:57], v[56:57], v[64:65] op_sel_hi:[1,0]
	v_pk_mul_f32 v[54:55], v[54:55], v[64:65] op_sel_hi:[1,0]
	v_pk_mul_f32 v[52:53], v[52:53], v[64:65] op_sel_hi:[1,0]
	v_pk_mul_f32 v[50:51], v[50:51], v[64:65] op_sel_hi:[1,0]
	v_pk_mul_f32 v[48:49], v[48:49], v[64:65] op_sel_hi:[1,0]
	v_pk_mul_f32 v[46:47], v[46:47], v[64:65] op_sel_hi:[1,0]
	v_pk_mul_f32 v[44:45], v[44:45], v[64:65] op_sel_hi:[1,0]
	v_pk_mul_f32 v[42:43], v[42:43], v[64:65] op_sel_hi:[1,0]
	v_pk_mul_f32 v[40:41], v[40:41], v[64:65] op_sel_hi:[1,0]
	v_pk_mul_f32 v[38:39], v[38:39], v[64:65] op_sel_hi:[1,0]
	v_pk_mul_f32 v[36:37], v[36:37], v[64:65] op_sel_hi:[1,0]
	v_pk_mul_f32 v[34:35], v[34:35], v[64:65] op_sel_hi:[1,0]
	v_pk_mul_f32 v[32:33], v[32:33], v[64:65] op_sel_hi:[1,0]
	v_pk_mul_f32 v[30:31], v[30:31], v[64:65] op_sel_hi:[1,0]
	v_pk_mul_f32 v[28:29], v[28:29], v[64:65] op_sel_hi:[1,0]
	v_pk_mul_f32 v[26:27], v[26:27], v[64:65] op_sel_hi:[1,0]
	v_pk_mul_f32 v[24:25], v[24:25], v[64:65] op_sel_hi:[1,0]
	v_pk_mul_f32 v[22:23], v[22:23], v[64:65] op_sel_hi:[1,0]
	v_pk_mul_f32 v[20:21], v[20:21], v[64:65] op_sel_hi:[1,0]
	v_pk_mul_f32 v[18:19], v[18:19], v[64:65] op_sel_hi:[1,0]
	v_pk_mul_f32 v[16:17], v[16:17], v[64:65] op_sel_hi:[1,0]
	v_pk_mul_f32 v[14:15], v[14:15], v[64:65] op_sel_hi:[1,0]
	v_pk_mul_f32 v[12:13], v[12:13], v[64:65] op_sel_hi:[1,0]
	v_pk_mul_f32 v[10:11], v[10:11], v[64:65] op_sel_hi:[1,0]
	v_pk_mul_f32 v[8:9], v[8:9], v[64:65] op_sel_hi:[1,0]
	v_pk_mul_f32 v[6:7], v[6:7], v[64:65] op_sel_hi:[1,0]
	v_pk_mul_f32 v[4:5], v[4:5], v[64:65] op_sel_hi:[1,0]
	v_pk_mul_f32 v[2:3], v[2:3], v[64:65] op_sel_hi:[1,0]
	v_pk_mul_f32 v[0:1], v[0:1], v[64:65] op_sel_hi:[1,0]
	s_branch .LBB0_503

; #define ALAS __attribute__((address_space(3)))
; __device__ __forceinline__ float ex2(float x) { return __builtin_amdgcn_exp2f(x); }
; template <int NDB> __device__ __forceinline__ void wait_v(bf16x8 (&v)[2 * NDB]) { if constexpr (NDB == 4) lds_wait8(v); else lds_wait4(v); }
; template <int NDB>
; __device__ __forceinline__ void softmax_pv(f32x16& s0, f32x16& s1, float& mref, float& lsum, f32x16 (&o)[NDB], const ALAS unsigned char* Vb, int r32, int hi) {
;     const unsigned vp = (unsigned)(uintptr_t)(Vb + r32 * ROWB + hi * 16);
;     bf16x8 va[2 * NDB], vb[2 * NDB];
;     issue_v<NDB, 0>(va, vp);
;     float ps = 0.f;
; #pragma unroll
;     for (int r = 0; r < 16; ++r) { s0[r] = ex2(s0[r]); ps += s0[r]; }
;     bf16x8 pf0, pf1, pf2, pf3;
;     pack16(s0, pf0, pf1);
;     wait_v<NDB>(va);
;     issue_v<NDB, 1>(vb, vp);
;     __builtin_amdgcn_sched_barrier(0);
; #pragma unroll
;     for (int d = 0; d < NDB; ++d) o[d] = __builtin_amdgcn_mfma_f32_32x32x16_bf16(va[d], pf0, o[d], 0, 0, 0);
; #pragma unroll
;     for (int d = 0; d < NDB; ++d) o[d] = __builtin_amdgcn_mfma_f32_32x32x16_bf16(va[NDB + d], pf1, o[d], 0, 0, 0);
; #pragma unroll
;     for (int r = 0; r < 16; ++r) { s1[r] = ex2(s1[r]); ps += s1[r]; }
;     pack16(s1, pf2, pf3);
; #pragma unroll
;     for (int i = 0; i < 2 * NDB; ++i) { __builtin_amdgcn_sched_group_barrier(0x008, 1, 0); __builtin_amdgcn_sched_group_barrier(0x002, (NDB == 4 ? 5 : 10), 0); }
;     __builtin_amdgcn_sched_barrier(0);
;     wait_v<NDB>(vb);
;     __builtin_amdgcn_sched_barrier(0);
; #pragma unroll
;     for (int d = 0; d < NDB; ++d) o[d] = __builtin_amdgcn_mfma_f32_32x32x16_bf16(vb[d], pf2, o[d], 0, 0, 0);
; #pragma unroll
;     for (int d = 0; d < NDB; ++d) o[d] = __builtin_amdgcn_mfma_f32_32x32x16_bf16(vb[NDB + d], pf3, o[d], 0, 0, 0);
;     lsum += ps;
;     if (__any(ps > 1048576.0f)) {
;         const float pt = ps + __shfl_xor(ps, 32); const float dl = pt > 1048576.0f ? floorf(__log2f(pt)) : 0.f, al = ex2(-dl); mref += dl; lsum *= al;
; #pragma unroll
;         for (int d = 0; d < NDB; ++d)
; #pragma unroll
;             for (int r = 0; r < 16; ++r) o[d][r] *= al;
;     }
.LBB0_544:
	v_add_u32_e32 v102, s17, v106
	v_add3_u32 v102, v102, v144, s95
	ds_read_b128 v[108:111], v102 offset:0
	ds_read_b128 v[112:115], v102 offset:4608
	ds_read_b128 v[116:119], v102 offset:32
	ds_read_b128 v[120:123], v102 offset:4640
	s_nop 7
	v_exp_f32_e32 v139, v56
	v_exp_f32_e32 v140, v57
	v_exp_f32_e32 v141, v58
	v_exp_f32_e32 v142, v59
	ds_read_b128 v[56:59], v102 offset:64
	v_exp_f32_e32 v143, v60
	v_exp_f32_e32 v156, v61
	v_exp_f32_e32 v157, v62
	v_exp_f32_e32 v158, v63
	ds_read_b128 v[60:63], v102 offset:4672
	v_exp_f32_e32 v103, v48
	v_exp_f32_e32 v132, v49
	v_exp_f32_e32 v133, v50
	v_exp_f32_e32 v134, v51
	v_exp_f32_e32 v135, v52
	v_exp_f32_e32 v136, v53
	v_exp_f32_e32 v137, v54
	v_exp_f32_e32 v138, v55
	ds_read_b128 v[124:127], v102 offset:96
	ds_read_b128 v[128:131], v102 offset:4704
	v_cvt_pk_bf16_f32 v48, v103, v132
	v_cvt_pk_bf16_f32 v49, v133, v134
	v_cvt_pk_bf16_f32 v50, v135, v136
	v_cvt_pk_bf16_f32 v51, v137, v138
	v_cvt_pk_bf16_f32 v52, v139, v140
	v_cvt_pk_bf16_f32 v53, v141, v142
	v_cvt_pk_bf16_f32 v54, v143, v156
	v_cvt_pk_bf16_f32 v55, v157, v158
	s_waitcnt lgkmcnt(4)
	v_mfma_f32_32x32x16_bf16 v[16:31], v[108:111], v[48:51], v[16:31]
	v_add_f32_e32 v102, 0, v103
	v_add_f32_e32 v102, v132, v102
	v_add_f32_e32 v102, v133, v102
	v_add_f32_e32 v102, v134, v102
	v_add_f32_e32 v102, v135, v102
	v_add_f32_e32 v102, v136, v102
	v_add_f32_e32 v102, v137, v102
	v_add_f32_e32 v102, v138, v102
	v_add_f32_e32 v102, v139, v102
	v_add_f32_e32 v102, v140, v102
	v_mfma_f32_32x32x16_bf16 v[0:15], v[112:115], v[48:51], v[0:15]
	v_add_f32_e32 v48, v141, v102
	v_add_f32_e32 v48, v142, v48
	v_add_f32_e32 v48, v143, v48
	v_exp_f32_e32 v49, v32
	v_add_f32_e32 v48, v156, v48
	v_exp_f32_e32 v50, v33
	v_add_f32_e32 v48, v157, v48
	v_exp_f32_e32 v51, v34
	v_add_f32_e32 v48, v158, v48
	v_exp_f32_e32 v102, v35
	v_exp_f32_e32 v103, v36
	v_add_f32_e32 v48, v49, v48
	v_exp_f32_e32 v108, v37
	v_add_f32_e32 v48, v50, v48
	v_exp_f32_e32 v109, v38
	v_exp_f32_e32 v110, v39
	v_exp_f32_e32 v40, v40
	v_exp_f32_e32 v41, v41
	v_exp_f32_e32 v42, v42
	v_exp_f32_e32 v43, v43
	v_exp_f32_e32 v44, v44
	v_exp_f32_e32 v45, v45
	v_exp_f32_e32 v46, v46
	v_exp_f32_e32 v47, v47
	v_add_f32_e32 v48, v51, v48
	v_add_f32_e32 v48, v102, v48
	v_add_f32_e32 v48, v103, v48
	v_add_f32_e32 v48, v108, v48
	v_cvt_pk_bf16_f32 v32, v49, v50
	v_cvt_pk_bf16_f32 v33, v51, v102
	v_cvt_pk_bf16_f32 v34, v103, v108
	v_cvt_pk_bf16_f32 v35, v109, v110
	v_mfma_f32_32x32x16_bf16 v[16:31], v[116:119], v[52:55], v[16:31]
	v_cvt_pk_bf16_f32 v36, v40, v41
	v_cvt_pk_bf16_f32 v37, v42, v43
	v_cvt_pk_bf16_f32 v38, v44, v45
	v_cvt_pk_bf16_f32 v39, v46, v47
	v_add_f32_e32 v48, v109, v48
	v_add_f32_e32 v48, v110, v48
	v_add_f32_e32 v40, v40, v48
	v_mfma_f32_32x32x16_bf16 v[0:15], v[120:123], v[52:55], v[0:15]
	v_add_f32_e32 v40, v41, v40
	v_add_f32_e32 v40, v42, v40
	v_add_f32_e32 v40, v43, v40
	v_add_f32_e32 v40, v44, v40
	v_add_f32_e32 v40, v45, v40
	v_add_f32_e32 v40, v46, v40
	s_waitcnt lgkmcnt(0)
	s_nop 0
	v_mfma_f32_32x32x16_bf16 v[16:31], v[56:59], v[32:35], v[16:31]
	v_mfma_f32_32x32x16_bf16 v[0:15], v[60:63], v[32:35], v[0:15]
	v_add_f32_e32 v32, v47, v40
	v_add_f32_e32 v100, v100, v32
	v_cmp_lt_f32_e32 vcc, s34, v32
	v_mfma_f32_32x32x16_bf16 v[16:31], v[124:127], v[36:39], v[16:31]
	v_mfma_f32_32x32x16_bf16 v[0:15], v[128:131], v[36:39], v[0:15]
	s_cbranch_vccz .LBB0_532
	ds_bpermute_b32 v33, v93, v32
	s_waitcnt lgkmcnt(0)
	v_add_f32_e32 v32, v32, v33
	v_log_f32_e32 v33, v32
	v_cmp_lt_f32_e32 vcc, s34, v32
	v_floor_f32_e32 v33, v33
	s_nop 0
	v_cndmask_b32_e32 v33, 0, v33, vcc
	v_exp_f32_e64 v32, -v33
	v_add_f32_e32 v101, v101, v33
	v_mul_f32_e32 v100, v100, v32
	v_pk_mul_f32 v[30:31], v[30:31], v[32:33] op_sel_hi:[1,0]
	v_pk_mul_f32 v[28:29], v[28:29], v[32:33] op_sel_hi:[1,0]
	v_pk_mul_f32 v[26:27], v[26:27], v[32:33] op_sel_hi:[1,0]
	v_pk_mul_f32 v[24:25], v[24:25], v[32:33] op_sel_hi:[1,0]
	v_pk_mul_f32 v[22:23], v[22:23], v[32:33] op_sel_hi:[1,0]
	v_pk_mul_f32 v[20:21], v[20:21], v[32:33] op_sel_hi:[1,0]
	v_pk_mul_f32 v[18:19], v[18:19], v[32:33] op_sel_hi:[1,0]
	v_pk_mul_f32 v[16:17], v[16:17], v[32:33] op_sel_hi:[1,0]
	v_pk_mul_f32 v[14:15], v[14:15], v[32:33] op_sel_hi:[1,0]
	v_pk_mul_f32 v[12:13], v[12:13], v[32:33] op_sel_hi:[1,0]
	v_pk_mul_f32 v[10:11], v[10:11], v[32:33] op_sel_hi:[1,0]
	v_pk_mul_f32 v[8:9], v[8:9], v[32:33] op_sel_hi:[1,0]
	v_pk_mul_f32 v[6:7], v[6:7], v[32:33] op_sel_hi:[1,0]
	v_pk_mul_f32 v[4:5], v[4:5], v[32:33] op_sel_hi:[1,0]
	v_pk_mul_f32 v[2:3], v[2:3], v[32:33] op_sel_hi:[1,0]
	v_pk_mul_f32 v[0:1], v[0:1], v[32:33] op_sel_hi:[1,0]
	s_branch .LBB0_532
